# attention step: the two waves of a SIMD issue their K/V tile DMAs at different points of the step (waves 0-3 after the QK segment, waves 4-7 before the exp segment)
# baseline (speedup 1.0000x reference)
.Lat_loop:
	s_cmp_ge_u32 s46, s45
	s_cbranch_scc1 .Lat_drain
	s_cmp_ge_u32 s46, s78
	s_cbranch_scc1 .Lat_lite_442
	s_lshl_b32 s60, s56, 1
	v_add_u32_e32 v250, s60, v245
	v_mfma_f32_32x32x16_bf16 v[128:143], v[208:211], v[16:19], v[160:175]
	v_add_f32_e32 v247, v247, v96
	v_add_f32_e32 v247, v247, v97
	v_add_f32_e32 v247, v247, v98
	v_add_f32_e32 v247, v247, v99
	v_cvt_pk_bf16_f32 v176, v96, v97
	v_cvt_pk_bf16_f32 v177, v98, v99
	v_mfma_f32_32x32x16_bf16 v[144:159], v[212:215], v[16:19], v[160:175]
	v_add_f32_e32 v247, v247, v100
	v_add_f32_e32 v247, v247, v101
	v_add_f32_e32 v247, v247, v102
	v_add_f32_e32 v247, v247, v103
	v_cvt_pk_bf16_f32 v178, v100, v101
	v_cvt_pk_bf16_f32 v179, v102, v103
	v_mfma_f32_32x32x16_bf16 v[128:143], v[216:219], v[20:23], v[128:143]
	v_add_f32_e32 v247, v247, v104
	v_add_f32_e32 v247, v247, v105
	v_add_f32_e32 v247, v247, v106
	v_add_f32_e32 v247, v247, v107
	v_cvt_pk_bf16_f32 v180, v104, v105
	v_cvt_pk_bf16_f32 v181, v106, v107
	v_mfma_f32_32x32x16_bf16 v[144:159], v[220:223], v[20:23], v[144:159]
	v_add_f32_e32 v247, v247, v108
	v_add_f32_e32 v247, v247, v109
	v_add_f32_e32 v247, v247, v110
	v_add_f32_e32 v247, v247, v111
	v_cvt_pk_bf16_f32 v182, v108, v109
	v_cvt_pk_bf16_f32 v183, v110, v111
	v_mfma_f32_32x32x16_bf16 v[128:143], v[224:227], v[24:27], v[128:143]
	v_add_f32_e32 v247, v247, v112
	v_add_f32_e32 v247, v247, v113
	v_add_f32_e32 v247, v247, v114
	v_add_f32_e32 v247, v247, v115
	v_cvt_pk_bf16_f32 v184, v112, v113
	v_cvt_pk_bf16_f32 v185, v114, v115
	v_mfma_f32_32x32x16_bf16 v[144:159], v[228:231], v[24:27], v[144:159]
	v_add_f32_e32 v247, v247, v116
	v_add_f32_e32 v247, v247, v117
	v_add_f32_e32 v247, v247, v118
	v_add_f32_e32 v247, v247, v119
	v_cvt_pk_bf16_f32 v186, v116, v117
	v_cvt_pk_bf16_f32 v187, v118, v119
	v_mfma_f32_32x32x16_bf16 v[128:143], v[232:235], v[28:31], v[128:143]
	v_add_f32_e32 v247, v247, v120
	v_add_f32_e32 v247, v247, v121
	v_add_f32_e32 v247, v247, v122
	v_add_f32_e32 v247, v247, v123
	v_cvt_pk_bf16_f32 v188, v120, v121
	v_cvt_pk_bf16_f32 v189, v122, v123
	ds_read_b64_tr_b16 v[192:193], v250 offset:0
	ds_read_b64_tr_b16 v[194:195], v250 offset:512
	v_mfma_f32_32x32x16_bf16 v[144:159], v[240:243], v[28:31], v[144:159]
	v_add_f32_e32 v247, v247, v124
	v_add_f32_e32 v247, v247, v125
	v_add_f32_e32 v247, v247, v126
	v_add_f32_e32 v247, v247, v127
	v_cvt_pk_bf16_f32 v190, v124, v125
	v_cvt_pk_bf16_f32 v191, v126, v127
	ds_read_b64_tr_b16 v[196:197], v250 offset:4096
	ds_read_b64_tr_b16 v[198:199], v250 offset:4608
	s_cmp_lt_u32 s47, 4
	s_cbranch_scc0 .Lat_dmaA_442
	s_add_i32 m0, s57, s70
	s_nop 0
	global_load_lds_dwordx4 v238, s[74:75]
	s_add_u32 s74, s74, 0x10000
	s_addc_u32 s75, s75, 0
	s_lshl_b32 s60, s58, 1
	s_add_i32 s60, s60, s71
	s_mov_b32 m0, s60
	s_nop 0
	global_load_lds_dwordx4 v239, s[76:77]
	s_add_u32 s62, s76, 0x80
	s_addc_u32 s63, s77, 0
	s_add_i32 m0, s60, 0x2000
	s_nop 0
	global_load_lds_dwordx4 v239, s[62:63]
	s_add_u32 s76, s76, 0x10000
	s_addc_u32 s77, s77, 0
.Lat_dmaA_442:
	s_cmp_lt_u32 s46, s72
	s_cbranch_scc1 .Lat_nomask_528
	s_sub_u32 s60, s46, s72
	s_lshl_b32 s60, s60, 6
	v_lshl_add_u32 v0, v252, 2, s60
	v_sub_u32_e32 v0, v246, v0
	v_mov_b32_e32 v1, 0xff800000
	v_cmp_gt_i32_e64 s[60:61], 0, v0
	v_cmp_gt_i32_e64 s[62:63], 32, v0
	v_cmp_gt_i32_e64 s[64:65], 1, v0
	v_cmp_gt_i32_e64 s[66:67], 33, v0
	v_cndmask_b32_e64 v128, v128, v1, s[60:61]
	v_cmp_gt_i32_e64 s[60:61], 2, v0
	v_cndmask_b32_e64 v144, v144, v1, s[62:63]
	v_cmp_gt_i32_e64 s[62:63], 34, v0
	v_cndmask_b32_e64 v129, v129, v1, s[64:65]
	v_cmp_gt_i32_e64 s[64:65], 3, v0
	v_cndmask_b32_e64 v145, v145, v1, s[66:67]
	v_cmp_gt_i32_e64 s[66:67], 35, v0
	v_cndmask_b32_e64 v130, v130, v1, s[60:61]
	v_cmp_gt_i32_e64 s[60:61], 8, v0
	v_cndmask_b32_e64 v146, v146, v1, s[62:63]
	v_cmp_gt_i32_e64 s[62:63], 40, v0
	v_cndmask_b32_e64 v131, v131, v1, s[64:65]
	v_cmp_gt_i32_e64 s[64:65], 9, v0
	v_cndmask_b32_e64 v147, v147, v1, s[66:67]
	v_cmp_gt_i32_e64 s[66:67], 41, v0
	v_cndmask_b32_e64 v132, v132, v1, s[60:61]
	v_cmp_gt_i32_e64 s[60:61], 10, v0
	v_cndmask_b32_e64 v148, v148, v1, s[62:63]
	v_cmp_gt_i32_e64 s[62:63], 42, v0
	v_cndmask_b32_e64 v133, v133, v1, s[64:65]
	v_cmp_gt_i32_e64 s[64:65], 11, v0
	v_cndmask_b32_e64 v149, v149, v1, s[66:67]
	v_cmp_gt_i32_e64 s[66:67], 43, v0
	v_cndmask_b32_e64 v134, v134, v1, s[60:61]
	v_cmp_gt_i32_e64 s[60:61], 16, v0
	v_cndmask_b32_e64 v150, v150, v1, s[62:63]
	v_cmp_gt_i32_e64 s[62:63], 48, v0
	v_cndmask_b32_e64 v135, v135, v1, s[64:65]
	v_cmp_gt_i32_e64 s[64:65], 17, v0
	v_cndmask_b32_e64 v151, v151, v1, s[66:67]
	v_cmp_gt_i32_e64 s[66:67], 49, v0
	v_cndmask_b32_e64 v136, v136, v1, s[60:61]
	v_cmp_gt_i32_e64 s[60:61], 18, v0
	v_cndmask_b32_e64 v152, v152, v1, s[62:63]
	v_cmp_gt_i32_e64 s[62:63], 50, v0
	v_cndmask_b32_e64 v137, v137, v1, s[64:65]
	v_cmp_gt_i32_e64 s[64:65], 19, v0
	v_cndmask_b32_e64 v153, v153, v1, s[66:67]
	v_cmp_gt_i32_e64 s[66:67], 51, v0
	v_cndmask_b32_e64 v138, v138, v1, s[60:61]
	v_cmp_gt_i32_e64 s[60:61], 24, v0
	v_cndmask_b32_e64 v154, v154, v1, s[62:63]
	v_cmp_gt_i32_e64 s[62:63], 56, v0
	v_cndmask_b32_e64 v139, v139, v1, s[64:65]
	v_cmp_gt_i32_e64 s[64:65], 25, v0
	v_cndmask_b32_e64 v155, v155, v1, s[66:67]
	v_cmp_gt_i32_e64 s[66:67], 57, v0
	v_cndmask_b32_e64 v140, v140, v1, s[60:61]
	v_cmp_gt_i32_e64 s[60:61], 26, v0
	v_cndmask_b32_e64 v156, v156, v1, s[62:63]
	v_cmp_gt_i32_e64 s[62:63], 58, v0
	v_cndmask_b32_e64 v141, v141, v1, s[64:65]
	v_cmp_gt_i32_e64 s[64:65], 27, v0
	v_cndmask_b32_e64 v157, v157, v1, s[66:67]
	v_cmp_gt_i32_e64 s[66:67], 59, v0
	v_cndmask_b32_e64 v142, v142, v1, s[60:61]
	s_nop 1
	v_cndmask_b32_e64 v158, v158, v1, s[62:63]
	v_cndmask_b32_e64 v143, v143, v1, s[64:65]
	v_cndmask_b32_e64 v159, v159, v1, s[66:67]

.Lat_noresc_442:
	s_cmp_ge_u32 s47, 4
	s_cbranch_scc0 .Lat_dmaB_442
	s_add_i32 m0, s57, s70
	s_nop 0
	global_load_lds_dwordx4 v238, s[74:75]
	s_add_u32 s74, s74, 0x10000
	s_addc_u32 s75, s75, 0
	s_lshl_b32 s60, s58, 1
	s_add_i32 s60, s60, s71
	s_mov_b32 m0, s60
	s_nop 0
	global_load_lds_dwordx4 v239, s[76:77]
	s_add_u32 s62, s76, 0x80
	s_addc_u32 s63, s77, 0
	s_add_i32 m0, s60, 0x2000
	s_nop 0
	global_load_lds_dwordx4 v239, s[62:63]
	s_add_u32 s76, s76, 0x10000
	s_addc_u32 s77, s77, 0

.Lat_norescO_442:
.Lat_next_442:
	s_cmp_ge_u32 s46, s45
	s_cbranch_scc1 .Lat_drain
	s_cmp_ge_u32 s46, s78
	s_cbranch_scc1 .Lat_lite_884
	s_lshl_b32 s60, s56, 1
	v_add_u32_e32 v250, s60, v245
	v_mfma_f32_32x32x16_bf16 v[96:111], v[208:211], v[16:19], v[160:175]
	v_add_f32_e32 v247, v247, v128
	v_add_f32_e32 v247, v247, v129
	v_add_f32_e32 v247, v247, v130
	v_add_f32_e32 v247, v247, v131
	v_cvt_pk_bf16_f32 v176, v128, v129
	v_cvt_pk_bf16_f32 v177, v130, v131
	v_mfma_f32_32x32x16_bf16 v[112:127], v[212:215], v[16:19], v[160:175]
	v_add_f32_e32 v247, v247, v132
	v_add_f32_e32 v247, v247, v133
	v_add_f32_e32 v247, v247, v134
	v_add_f32_e32 v247, v247, v135
	v_cvt_pk_bf16_f32 v178, v132, v133
	v_cvt_pk_bf16_f32 v179, v134, v135
	v_mfma_f32_32x32x16_bf16 v[96:111], v[216:219], v[20:23], v[96:111]
	v_add_f32_e32 v247, v247, v136
	v_add_f32_e32 v247, v247, v137
	v_add_f32_e32 v247, v247, v138
	v_add_f32_e32 v247, v247, v139
	v_cvt_pk_bf16_f32 v180, v136, v137
	v_cvt_pk_bf16_f32 v181, v138, v139
	v_mfma_f32_32x32x16_bf16 v[112:127], v[220:223], v[20:23], v[112:127]
	v_add_f32_e32 v247, v247, v140
	v_add_f32_e32 v247, v247, v141
	v_add_f32_e32 v247, v247, v142
	v_add_f32_e32 v247, v247, v143
	v_cvt_pk_bf16_f32 v182, v140, v141
	v_cvt_pk_bf16_f32 v183, v142, v143
	v_mfma_f32_32x32x16_bf16 v[96:111], v[224:227], v[24:27], v[96:111]
	v_add_f32_e32 v247, v247, v144
	v_add_f32_e32 v247, v247, v145
	v_add_f32_e32 v247, v247, v146
	v_add_f32_e32 v247, v247, v147
	v_cvt_pk_bf16_f32 v184, v144, v145
	v_cvt_pk_bf16_f32 v185, v146, v147
	v_mfma_f32_32x32x16_bf16 v[112:127], v[228:231], v[24:27], v[112:127]
	v_add_f32_e32 v247, v247, v148
	v_add_f32_e32 v247, v247, v149
	v_add_f32_e32 v247, v247, v150
	v_add_f32_e32 v247, v247, v151
	v_cvt_pk_bf16_f32 v186, v148, v149
	v_cvt_pk_bf16_f32 v187, v150, v151
	v_mfma_f32_32x32x16_bf16 v[96:111], v[232:235], v[28:31], v[96:111]
	v_add_f32_e32 v247, v247, v152
	v_add_f32_e32 v247, v247, v153
	v_add_f32_e32 v247, v247, v154
	v_add_f32_e32 v247, v247, v155
	v_cvt_pk_bf16_f32 v188, v152, v153
	v_cvt_pk_bf16_f32 v189, v154, v155
	ds_read_b64_tr_b16 v[192:193], v250 offset:0
	ds_read_b64_tr_b16 v[194:195], v250 offset:512
	v_mfma_f32_32x32x16_bf16 v[112:127], v[240:243], v[28:31], v[112:127]
	v_add_f32_e32 v247, v247, v156
	v_add_f32_e32 v247, v247, v157
	v_add_f32_e32 v247, v247, v158
	v_add_f32_e32 v247, v247, v159
	v_cvt_pk_bf16_f32 v190, v156, v157
	v_cvt_pk_bf16_f32 v191, v158, v159
	ds_read_b64_tr_b16 v[196:197], v250 offset:4096
	ds_read_b64_tr_b16 v[198:199], v250 offset:4608
	s_cmp_lt_u32 s47, 4
	s_cbranch_scc0 .Lat_dmaA_884
	s_add_i32 m0, s57, s70
	s_nop 0
	global_load_lds_dwordx4 v238, s[74:75]
	s_add_u32 s74, s74, 0x10000
	s_addc_u32 s75, s75, 0
	s_lshl_b32 s60, s58, 1
	s_add_i32 s60, s60, s71
	s_mov_b32 m0, s60
	s_nop 0
	global_load_lds_dwordx4 v239, s[76:77]
	s_add_u32 s62, s76, 0x80
	s_addc_u32 s63, s77, 0
	s_add_i32 m0, s60, 0x2000
	s_nop 0
	global_load_lds_dwordx4 v239, s[62:63]
	s_add_u32 s76, s76, 0x10000
	s_addc_u32 s77, s77, 0
.Lat_dmaA_884:
	s_cmp_lt_u32 s46, s72
	s_cbranch_scc1 .Lat_nomask_970
	s_sub_u32 s60, s46, s72
	s_lshl_b32 s60, s60, 6
	v_lshl_add_u32 v0, v252, 2, s60
	v_sub_u32_e32 v0, v246, v0
	v_mov_b32_e32 v1, 0xff800000
	v_cmp_gt_i32_e64 s[60:61], 0, v0
	v_cmp_gt_i32_e64 s[62:63], 32, v0
	v_cmp_gt_i32_e64 s[64:65], 1, v0
	v_cmp_gt_i32_e64 s[66:67], 33, v0
	v_cndmask_b32_e64 v96, v96, v1, s[60:61]
	v_cmp_gt_i32_e64 s[60:61], 2, v0
	v_cndmask_b32_e64 v112, v112, v1, s[62:63]
	v_cmp_gt_i32_e64 s[62:63], 34, v0
	v_cndmask_b32_e64 v97, v97, v1, s[64:65]
	v_cmp_gt_i32_e64 s[64:65], 3, v0
	v_cndmask_b32_e64 v113, v113, v1, s[66:67]
	v_cmp_gt_i32_e64 s[66:67], 35, v0
	v_cndmask_b32_e64 v98, v98, v1, s[60:61]
	v_cmp_gt_i32_e64 s[60:61], 8, v0
	v_cndmask_b32_e64 v114, v114, v1, s[62:63]
	v_cmp_gt_i32_e64 s[62:63], 40, v0
	v_cndmask_b32_e64 v99, v99, v1, s[64:65]
	v_cmp_gt_i32_e64 s[64:65], 9, v0
	v_cndmask_b32_e64 v115, v115, v1, s[66:67]
	v_cmp_gt_i32_e64 s[66:67], 41, v0
	v_cndmask_b32_e64 v100, v100, v1, s[60:61]
	v_cmp_gt_i32_e64 s[60:61], 10, v0
	v_cndmask_b32_e64 v116, v116, v1, s[62:63]
	v_cmp_gt_i32_e64 s[62:63], 42, v0
	v_cndmask_b32_e64 v101, v101, v1, s[64:65]
	v_cmp_gt_i32_e64 s[64:65], 11, v0
	v_cndmask_b32_e64 v117, v117, v1, s[66:67]
	v_cmp_gt_i32_e64 s[66:67], 43, v0
	v_cndmask_b32_e64 v102, v102, v1, s[60:61]
	v_cmp_gt_i32_e64 s[60:61], 16, v0
	v_cndmask_b32_e64 v118, v118, v1, s[62:63]
	v_cmp_gt_i32_e64 s[62:63], 48, v0
	v_cndmask_b32_e64 v103, v103, v1, s[64:65]
	v_cmp_gt_i32_e64 s[64:65], 17, v0
	v_cndmask_b32_e64 v119, v119, v1, s[66:67]
	v_cmp_gt_i32_e64 s[66:67], 49, v0
	v_cndmask_b32_e64 v104, v104, v1, s[60:61]
	v_cmp_gt_i32_e64 s[60:61], 18, v0
	v_cndmask_b32_e64 v120, v120, v1, s[62:63]
	v_cmp_gt_i32_e64 s[62:63], 50, v0
	v_cndmask_b32_e64 v105, v105, v1, s[64:65]
	v_cmp_gt_i32_e64 s[64:65], 19, v0
	v_cndmask_b32_e64 v121, v121, v1, s[66:67]
	v_cmp_gt_i32_e64 s[66:67], 51, v0
	v_cndmask_b32_e64 v106, v106, v1, s[60:61]
	v_cmp_gt_i32_e64 s[60:61], 24, v0
	v_cndmask_b32_e64 v122, v122, v1, s[62:63]
	v_cmp_gt_i32_e64 s[62:63], 56, v0
	v_cndmask_b32_e64 v107, v107, v1, s[64:65]
	v_cmp_gt_i32_e64 s[64:65], 25, v0
	v_cndmask_b32_e64 v123, v123, v1, s[66:67]
	v_cmp_gt_i32_e64 s[66:67], 57, v0
	v_cndmask_b32_e64 v108, v108, v1, s[60:61]
	v_cmp_gt_i32_e64 s[60:61], 26, v0
	v_cndmask_b32_e64 v124, v124, v1, s[62:63]
	v_cmp_gt_i32_e64 s[62:63], 58, v0
	v_cndmask_b32_e64 v109, v109, v1, s[64:65]
	v_cmp_gt_i32_e64 s[64:65], 27, v0
	v_cndmask_b32_e64 v125, v125, v1, s[66:67]
	v_cmp_gt_i32_e64 s[66:67], 59, v0
	v_cndmask_b32_e64 v110, v110, v1, s[60:61]
	s_nop 1
	v_cndmask_b32_e64 v126, v126, v1, s[62:63]
	v_cndmask_b32_e64 v111, v111, v1, s[64:65]
	v_cndmask_b32_e64 v127, v127, v1, s[66:67]
